# blocked H layout + B-row remap in P4 so each wave writes full 128B lines (bj halves adjacent)
# baseline (speedup 1.0000x reference)
; #define PG8_STAGE(bufoff, gbase, voff) do { _Pragma("unroll") for (int _i = 0; _i < 2; ++_i) \
;         __builtin_amdgcn_global_load_lds((const unsigned*)((const char*)(gbase) + (voff)[_i]), (PG8_LAS unsigned*)(lds + (bufoff) + ldsw + _i * 8192), 16, 0, 0); } while (0)
; #define PG8_WAIT_V(n) asm volatile("s_waitcnt vmcnt(" #n ")" ::: "memory")
; #define PG8_BAR __builtin_amdgcn_s_barrier()
; template <class Epi, class Sched, bool ALIGN_EPI = false, bool SP2 = false>
; __device__ __forceinline__ void gemm_phase(PG8_LAS unsigned char* lds, const Gemm g, const Sched& S, const Epi& E) {
;     const int tid = threadIdx.x, wid = __builtin_amdgcn_readfirstlane(tid >> 6), lane = tid & 63, wr = wid >> 2, wc = wid & 3, fr = lane & 15, fq = lane >> 4;
;     const int K = g.K, nt = K / BK;
;     unsigned voffA[2], voffB[2];
; #pragma unroll
;     for (int i = 0; i < 2; ++i) { int R, C; stage_rc(tid * 16 + i * 8192, R, C); const int Rb = Epi::PERM ? ((R & ~31) + perm32(R & 31)) : R;
;         voffA[i] = (unsigned)(R * K + C) * 2u; voffB[i] = (unsigned)(Rb * K + C) * 2u; }
;     const size_t kstep = (size_t)(BK * 2);
;     const size_t hstep = (size_t)HALF * K * 2;
;     const size_t tstep = 2 * hstep;
;     const unsigned ldsw = (unsigned)wid * 1024u;
;     const int aoff = lds_byte(wr * 64 + fr, fq * 8), boff = lds_byte(wc * 32 + fr, fq * 8);
;     ...
;     Unit cur, nxt; int ui = 0;
;     if (!S.next(0, cur)) return;
;     f32x4 acc[2][2][4][2];
; #pragma unroll
;     for (int a = 0; a < 2; ++a)
; #pragma unroll
;         for (int b = 0; b < 2; ++b)
; #pragma unroll
;             for (int m = 0; m < 4; ++m)
; #pragma unroll
;                 for (int n = 0; n < 2; ++n) acc[a][b][m][n] = (f32x4){0.f, 0.f, 0.f, 0.f};
;     bf16x8 At[4][2], B0[2][2], B1[2][2];
;     const char* cA = (const char*)g.A + (size_t)cur.pm * tstep; const char* cB = (const char*)g.Bt + (size_t)cur.pn * tstep;
;     S.a_ready(cur);
;     if constexpr (SP2) {
;         PG8_STAGE(PG8_SB(0, 0), cB, voffB); PG8_STAGE(PG8_SB(0, 1), cB + hstep, voffB); PG8_STAGE(PG8_SA(0, 0), cA, voffA); PG8_STAGE(PG8_SA(0, 1), cA + hstep, voffA);
;         if (wr == 1) PG8_BAR;
;         PG8_WAIT_V(2); PG8_BAR;
;         PG8_STAGE(PG8_SB(1, 0), cB + kstep, voffB); PG8_STAGE(PG8_SA(1, 0), cA + kstep, voffA); PG8_STAGE(PG8_SB(1, 1), cB + hstep + kstep, voffB);
;         PG8_WAIT_V(6); PG8_BAR;
.LBB0_1371:
	v_lshrrev_b32_e32 v3, 1, v208
	v_lshrrev_b32_e32 v4, 5, v208
	v_and_b32_e32 v3, 24, v3
	v_and_b32_e32 v4, 4, v4
	v_bfe_u32 v5, v208, 2, 2
	v_lshlrev_b32_e32 v1, 4, v208
	v_and_b32_e32 v2, 32, v208
	v_bfe_u32 v12, v208, 2, 4
	v_or3_b32 v3, v4, v5, v3
	v_lshrrev_b32_e32 v4, 3, v208
	s_movk_i32 s0, 0x70
	v_bitop3_b32 v10, v1, v2, 48 bitop3:0x6c
	v_and_b32_e32 v11, 64, v208
	v_and_or_b32 v5, v4, s0, v12
	s_movk_i32 s0, 0x60
	v_add_u32_e32 v13, 0x2000, v1
	v_or_b32_e32 v2, v10, v11
	v_and_b32_e32 v4, 0x60, v4
	v_lshl_or_b32 v4, v4, 1, v3
	v_lshrrev_b32_e32 v1, 7, v13
	s_movk_i32 s0, 0xf0
	v_lshl_or_b32 v132, v4, 11, v2
	v_and_or_b32 v4, v1, s0, v12
	s_movk_i32 s0, 0xe0
	s_lshr_b32 s10, s12, 6
	s_ashr_i32 s25, s24, 31
	s_ashr_i32 s23, s22, 31
	s_lshr_b32 s14, s12, 8
	v_and_b32_e32 v1, 0xe0, v1
	v_lshl_or_b32 v1, v1, 1, v3
	s_lshl_b32 s31, s10, 10
	s_lshl_b64 s[0:1], s[24:25], 19
	s_lshl_b64 s[4:5], s[22:23], 19
	s_add_u32 s26, s74, s4
	s_addc_u32 s27, s75, s5
	s_add_i32 s34, s31, 0x100
	s_add_i32 m0, s34, 0x10000
	v_lshl_or_b32 v136, v1, 11, v2
	global_load_lds_dwordx4 v132, s[26:27]
	s_add_i32 m0, s34, 0x12000
	s_add_u32 s4, s26, 0x10000
	global_load_lds_dwordx4 v136, s[26:27]
	s_addc_u32 s5, s27, 0
	s_add_i32 m0, s34, 0x14000
	v_lshl_or_b32 v130, v5, 11, v2
	global_load_lds_dwordx4 v132, s[4:5]
	s_add_i32 m0, s34, 0x16000
	v_lshl_or_b32 v134, v4, 11, v2
	global_load_lds_dwordx4 v136, s[4:5]
	s_add_u32 s4, s66, s0
	s_addc_u32 s5, s67, s1
	s_add_i32 s35, s34, 0x2000
	s_mov_b32 m0, s34
	s_add_u32 s0, s4, 0x40000
	global_load_lds_dwordx4 v130, s[4:5]
	s_mov_b32 m0, s35
	s_addc_u32 s1, s5, 0
	s_add_i32 s36, s34, 0x4000
	global_load_lds_dwordx4 v134, s[4:5]
	s_mov_b32 m0, s36
	s_add_i32 s37, s34, 0x6000
	global_load_lds_dwordx4 v130, s[0:1]
	s_mov_b32 m0, s37
	v_mov_b32_e32 v133, 0
	global_load_lds_dwordx4 v134, s[0:1]
	v_mov_b32_e32 v137, v133
	v_mov_b32_e32 v131, v133
	v_mov_b32_e32 v135, v133
	s_cmp_eq_u32 s14, 1
	s_mov_b32 s15, 0x10000
	v_lshl_add_u64 v[8:9], s[26:27], 0, v[132:133]
	v_lshl_add_u64 v[4:5], s[26:27], 0, v[136:137]
	s_mov_b32 s16, 0x14000
	v_lshl_add_u64 v[2:3], s[4:5], 0, v[130:131]
	s_cselect_b64 s[6:7], -1, 0
	s_cmp_lg_u32 s14, 1
	v_lshl_add_u64 v[6:7], s[4:5], 0, v[134:135]
	s_cbranch_scc1 .LBB0_1373
	s_barrier
.LBB0_1373:
	s_lshl_b32 s0, s10, 5
	s_mov_b64 s[10:11], 0x80
	s_and_b32 s17, s0, 0x60
	s_lshl_b32 s70, s17, 9
	s_add_i32 m0, s34, 0x18000
	v_lshl_add_u64 v[8:9], v[8:9], 0, s[10:11]
	s_lshl_b32 s13, s14, 13
	s_lshl_b32 s18, s17, 7
	s_waitcnt vmcnt(2)
	s_barrier
	global_load_lds_dwordx4 v[8:9], off
	v_lshl_add_u64 v[4:5], v[4:5], 0, s[10:11]
	s_add_i32 m0, s34, 0x1a000
	s_add_i32 s38, s34, 0x8000
	s_add_i32 s39, s34, 0xa000
	global_load_lds_dwordx4 v[4:5], off
	v_lshl_add_u64 v[2:3], v[2:3], 0, s[10:11]
	s_mov_b32 m0, s38
	s_add_u32 s0, s26, 0x10080
	global_load_lds_dwordx4 v[2:3], off
	v_lshl_add_u64 v[2:3], v[6:7], 0, s[10:11]
	s_mov_b32 m0, s39
	s_addc_u32 s1, s27, 0
	global_load_lds_dwordx4 v[2:3], off
	s_add_i32 m0, s34, 0x1c000
	v_lshl_add_u64 v[2:3], s[0:1], 0, v[132:133]
	global_load_lds_dwordx4 v[2:3], off
	v_lshl_add_u64 v[2:3], s[0:1], 0, v[136:137]
	s_add_i32 m0, s34, 0x1e000
	v_bfe_u32 v4, v208, 4, 2
	global_load_lds_dwordx4 v[2:3], off
	v_and_b32_e32 v3, 15, v208
	v_lshlrev_b32_e32 v2, 4, v4
	v_lshlrev_b32_e32 v6, 2, v3
	v_lshl_or_b32 v1, s14, 6, v3
	v_lshl_or_b32 v5, v3, 6, v2
	v_and_b32_e32 v3, 32, v6
	v_bitop3_b32 v5, v5, s13, v3 bitop3:0xde
	v_lshlrev_b32_e32 v3, 6, v208
	s_movk_i32 s0, 0x3c0
	v_lshlrev_b32_e32 v7, 2, v208
	v_and_or_b32 v3, v3, s0, v2
	v_and_b32_e32 v7, 32, v7
	v_bitop3_b32 v7, s18, v3, v7 bitop3:0xf6
	v_mov_b32_e32 v3, v133
	v_lshl_add_u64 v[138:139], s[8:9], 0, v[2:3]
	v_lshlrev_b32_e32 v2, 8, v208
	v_and_b32_e32 v2, 0x38000, v2
	v_lshlrev_b32_e32 v3, 11, v12
	v_or3_b32 v2, v10, v2, v3
	s_cmpk_lt_u32 s12, 0x100
	v_add_u32_e32 v140, v2, v11
	v_lshlrev_b32_e32 v2, 4, v13
	s_cselect_b64 s[12:13], -1, 0
	s_lshl_b32 s8, s14, 8
	v_and_b32_e32 v2, 0x78000, v2
	s_mov_b32 s0, 0x18000
	s_mov_b32 s1, 0x1c000
	s_waitcnt vmcnt(6)
	s_addk_i32 s8, 0x100
	v_or3_b32 v2, v10, v2, v3
	s_add_i32 s8, s8, 0x20800
	v_add_u32_e32 v142, v2, v11
	s_add_i32 s41, s15, 0x100
	s_add_i32 s44, s16, 0x100
	s_add_i32 s45, s0, 0x100
	s_add_i32 s46, s1, 0x100
	v_mbcnt_lo_u32_b32 v2, -1, 0
	v_add_u32_e32 v151, s8, v6
	v_lshl_or_b32 v152, v4, 3, s70
	v_mov_b32_e32 v141, v133
	v_mov_b32_e32 v143, v133
	s_mov_b32 s23, 0
	s_movk_i32 s40, 0x181
	v_add_u32_e32 v153, s41, v7
	v_add_u32_e32 v154, s44, v7
	v_add_u32_e32 v155, 0x100, v5
	v_mov_b32_e32 v156, 0x358637bd
	v_mov_b64_e32 v[144:145], 0xbff
	v_add_u32_e32 v157, s45, v7
	v_add_u32_e32 v158, s46, v7
	v_mbcnt_hi_u32_b32 v159, -1, v2
	s_mov_b32 s47, 0
	s_barrier
	s_branch .LBB0_1376

; #define PG8_STAGE(bufoff, gbase, voff) do { _Pragma("unroll") for (int _i = 0; _i < 2; ++_i) \
;         __builtin_amdgcn_global_load_lds((const unsigned*)((const char*)(gbase) + (voff)[_i]), (PG8_LAS unsigned*)(lds + (bufoff) + ldsw + _i * 8192), 16, 0, 0); } while (0)
; #define PG8_LDA(dst, b, h) do { _Pragma("unroll") for (int m = 0; m < 4; ++m) _Pragma("unroll") for (int k = 0; k < 2; ++k) dst[m][k] = *(const PG8_LAS bf16x8*)(lds + PG8_SA(b, h) + aoff + m * 2048 + k * 1024); } while (0)
; #define PG8_LDB(dst, b, h) do { _Pragma("unroll") for (int n = 0; n < 2; ++n) _Pragma("unroll") for (int k = 0; k < 2; ++k) dst[n][k] = *(const PG8_LAS bf16x8*)(lds + PG8_SB(b, h) + boff + n * 2048 + k * 1024); } while (0)
; #define PG8_MMA(ai, bj, At, Bt) do { __builtin_amdgcn_s_setprio(1); _Pragma("unroll") for (int m = 0; m < 4; ++m) _Pragma("unroll") for (int n = 0; n < 2; ++n) _Pragma("unroll") for (int k = 0; k < 2; ++k) \
;         acc[ai][bj][m][n] = __builtin_amdgcn_mfma_f32_16x16x32_bf16(Bt[n][k], At[m][k], acc[ai][bj][m][n], 0, 0, 0); __builtin_amdgcn_s_setprio(0); } while (0)
; #define PG8_WAIT_V(n) asm volatile("s_waitcnt vmcnt(" #n ")" ::: "memory")
; #define PG8_WAIT_L(n) asm volatile("s_waitcnt lgkmcnt(" #n ")" ::: "memory")
; #define PG8_BAR __builtin_amdgcn_s_barrier()
; #define PG8_SCHED __builtin_amdgcn_sched_barrier(0)
; template <class Epi, class Sched, bool ALIGN_EPI = false, bool SP2 = false>
; __device__ __forceinline__ void gemm_phase(PG8_LAS unsigned char* lds, const Gemm g, const Sched& S, const Epi& E) {
;     ...
;             const bool last = (t == nt - 2);
;             const char* a1 = cA + (size_t)(t + 1) * kstep;
;             const char* a2 = last ? nA : cA + (size_t)(t + 2) * kstep; const char* b2 = last ? nB : cB + (size_t)(t + 2) * kstep;
;             const char* a3 = a2 + kstep; const char* b3 = b2 + kstep;
;             if (last && has_next) S.a_ready(nxt);
;             if constexpr (SP2) {
;             PG8_LDB(B0, 0, 0); PG8_LDB(B1, 0, 1); PG8_SCHED; PG8_LDA(At, 0, 0); PG8_STAGE(PG8_SA(1, 1), a1 + hstep, voffA);
;             PG8_WAIT_V(8); PG8_WAIT_L(0); PG8_BAR; PG8_MMA(0, 0, At, B0); PG8_MMA(0, 1, At, B1); PG8_BAR; PG8_SCHED;
;             PG8_LDA(At, 0, 1); PG8_STAGE(PG8_SB(0, 0), b2, voffB); PG8_STAGE(PG8_SB(0, 1), b2 + hstep, voffB); PG8_STAGE(PG8_SA(0, 0), a2, voffA);
.LBB0_1380:
	ds_read_b128 v[146:149], v153
	ds_read_b128 v[160:163], v153 offset:1024
	ds_read_b128 v[164:167], v153 offset:2048
	ds_read_b128 v[168:171], v153 offset:3072
	ds_read_b128 v[172:175], v154
	ds_read_b128 v[176:179], v154 offset:1024
	ds_read_b128 v[180:183], v154 offset:2048
	ds_read_b128 v[184:187], v154 offset:3072
	s_add_u32 s0, s4, 0xfffc0080
	s_addc_u32 s1, s5, -1
	s_cmp_eq_u32 s54, 12
	s_cselect_b32 s29, s15, s1
	s_cselect_b32 s28, s25, s0
	s_cselect_b32 s27, s9, s53
	s_cselect_b32 s26, s49, s52
	v_lshl_add_u64 v[222:223], s[4:5], 0, v[140:141]
	s_add_i32 m0, s34, 0xc000
	ds_read_b128 v[188:191], v155
	ds_read_b128 v[192:195], v155 offset:1024
	ds_read_b128 v[196:199], v155 offset:2048
	ds_read_b128 v[200:203], v155 offset:3072
	ds_read_b128 v[204:207], v155 offset:4096
	ds_read_b128 v[210:213], v155 offset:5120
	ds_read_b128 v[214:217], v155 offset:6144
	ds_read_b128 v[218:221], v155 offset:7168
	global_load_lds_dwordx4 v[222:223], off
	v_lshl_add_u64 v[222:223], s[4:5], 0, v[142:143]
	s_add_i32 m0, s34, 0xe000
	s_nop 0
	global_load_lds_dwordx4 v[222:223], off
	s_waitcnt vmcnt(8)
	s_waitcnt lgkmcnt(0)
	s_barrier
	s_setprio 1
	s_waitcnt lgkmcnt(0)
	v_mfma_f32_16x16x32_bf16 v[126:129], v[146:149], v[188:191], v[126:129]
	v_mfma_f32_16x16x32_bf16 v[122:125], v[164:167], v[188:191], v[122:125]
	v_mfma_f32_16x16x32_bf16 v[110:113], v[146:149], v[196:199], v[110:113]
	v_mfma_f32_16x16x32_bf16 v[106:109], v[164:167], v[196:199], v[106:109]
	v_mfma_f32_16x16x32_bf16 v[94:97], v[146:149], v[204:207], v[94:97]
	v_mfma_f32_16x16x32_bf16 v[90:93], v[164:167], v[204:207], v[90:93]
	v_mfma_f32_16x16x32_bf16 v[78:81], v[146:149], v[214:217], v[78:81]
	v_mfma_f32_16x16x32_bf16 v[74:77], v[164:167], v[214:217], v[74:77]
	v_mfma_f32_16x16x32_bf16 v[126:129], v[160:163], v[192:195], v[126:129]
	v_mfma_f32_16x16x32_bf16 v[122:125], v[168:171], v[192:195], v[122:125]
	v_mfma_f32_16x16x32_bf16 v[110:113], v[160:163], v[200:203], v[110:113]
	v_mfma_f32_16x16x32_bf16 v[106:109], v[168:171], v[200:203], v[106:109]
	v_mfma_f32_16x16x32_bf16 v[94:97], v[160:163], v[210:213], v[94:97]
	v_mfma_f32_16x16x32_bf16 v[90:93], v[168:171], v[210:213], v[90:93]
	v_mfma_f32_16x16x32_bf16 v[78:81], v[160:163], v[218:221], v[78:81]
	v_mfma_f32_16x16x32_bf16 v[74:77], v[168:171], v[218:221], v[74:77]
	s_setprio 0
	s_setprio 1
	v_mfma_f32_16x16x32_bf16 v[118:121], v[172:175], v[188:191], v[118:121]
	v_mfma_f32_16x16x32_bf16 v[114:117], v[180:183], v[188:191], v[114:117]
	v_mfma_f32_16x16x32_bf16 v[102:105], v[172:175], v[196:199], v[102:105]
	v_mfma_f32_16x16x32_bf16 v[98:101], v[180:183], v[196:199], v[98:101]
	v_mfma_f32_16x16x32_bf16 v[86:89], v[172:175], v[204:207], v[86:89]
	v_mfma_f32_16x16x32_bf16 v[82:85], v[180:183], v[204:207], v[82:85]
	v_mfma_f32_16x16x32_bf16 v[70:73], v[172:175], v[214:217], v[70:73]
	v_mfma_f32_16x16x32_bf16 v[66:69], v[180:183], v[214:217], v[66:69]
	v_mfma_f32_16x16x32_bf16 v[118:121], v[176:179], v[192:195], v[118:121]
	v_mfma_f32_16x16x32_bf16 v[114:117], v[184:187], v[192:195], v[114:117]
	v_mfma_f32_16x16x32_bf16 v[102:105], v[176:179], v[200:203], v[102:105]
	v_mfma_f32_16x16x32_bf16 v[98:101], v[184:187], v[200:203], v[98:101]
	v_mfma_f32_16x16x32_bf16 v[86:89], v[176:179], v[210:213], v[86:89]
	v_mfma_f32_16x16x32_bf16 v[82:85], v[184:187], v[210:213], v[82:85]
	v_mfma_f32_16x16x32_bf16 v[70:73], v[176:179], v[218:221], v[70:73]
	v_mfma_f32_16x16x32_bf16 v[66:69], v[184:187], v[218:221], v[66:69]
	s_setprio 0
	s_barrier
	s_add_i32 s0, s41, s31
	v_lshl_add_u64 v[222:223], s[26:27], 0, v[132:133]
	s_mov_b32 m0, s0
	ds_read_b128 v[188:191], v155 offset:16384
	ds_read_b128 v[192:195], v155 offset:17408
	ds_read_b128 v[196:199], v155 offset:18432
	ds_read_b128 v[200:203], v155 offset:19456
	ds_read_b128 v[204:207], v155 offset:20480
	ds_read_b128 v[210:213], v155 offset:21504
	ds_read_b128 v[214:217], v155 offset:22528
	ds_read_b128 v[218:221], v155 offset:23552
	global_load_lds_dwordx4 v[222:223], off
	s_add_i32 m0, s0, 0x2000
	s_add_u32 s0, s26, 0x10000
	v_lshl_add_u64 v[224:225], s[26:27], 0, v[136:137]
	s_addc_u32 s1, s27, 0
	s_add_i32 s55, s44, s31
	global_load_lds_dwordx4 v[224:225], off
	v_lshl_add_u64 v[226:227], s[0:1], 0, v[132:133]
	s_mov_b32 m0, s55
	v_lshl_add_u64 v[228:229], s[28:29], 0, v[134:135]
	global_load_lds_dwordx4 v[226:227], off
	v_lshl_add_u64 v[226:227], s[0:1], 0, v[136:137]
	s_add_i32 m0, s55, 0x2000
	s_nop 0
	global_load_lds_dwordx4 v[226:227], off
	v_lshl_add_u64 v[226:227], s[28:29], 0, v[130:131]
	s_mov_b32 m0, s34
	s_nop 0
	global_load_lds_dwordx4 v[226:227], off
	s_mov_b32 m0, s35
	s_nop 0
	global_load_lds_dwordx4 v[228:229], off
	s_waitcnt vmcnt(8)
	s_waitcnt lgkmcnt(0)
	s_barrier
; #define PG8_STAGE(bufoff, gbase, voff) do { _Pragma("unroll") for (int _i = 0; _i < 2; ++_i) \
;         __builtin_amdgcn_global_load_lds((const unsigned*)((const char*)(gbase) + (voff)[_i]), (PG8_LAS unsigned*)(lds + (bufoff) + ldsw + _i * 8192), 16, 0, 0); } while (0)
; #define PG8_LDA(dst, b, h) do { _Pragma("unroll") for (int m = 0; m < 4; ++m) _Pragma("unroll") for (int k = 0; k < 2; ++k) dst[m][k] = *(const PG8_LAS bf16x8*)(lds + PG8_SA(b, h) + aoff + m * 2048 + k * 1024); } while (0)
; #define PG8_LDB(dst, b, h) do { _Pragma("unroll") for (int n = 0; n < 2; ++n) _Pragma("unroll") for (int k = 0; k < 2; ++k) dst[n][k] = *(const PG8_LAS bf16x8*)(lds + PG8_SB(b, h) + boff + n * 2048 + k * 1024); } while (0)
; #define PG8_MMA(ai, bj, At, Bt) do { __builtin_amdgcn_s_setprio(1); _Pragma("unroll") for (int m = 0; m < 4; ++m) _Pragma("unroll") for (int n = 0; n < 2; ++n) _Pragma("unroll") for (int k = 0; k < 2; ++k) \
;         acc[ai][bj][m][n] = __builtin_amdgcn_mfma_f32_16x16x32_bf16(Bt[n][k], At[m][k], acc[ai][bj][m][n], 0, 0, 0); __builtin_amdgcn_s_setprio(0); } while (0)
; #define PG8_WAIT_V(n) asm volatile("s_waitcnt vmcnt(" #n ")" ::: "memory")
; #define PG8_WAIT_L(n) asm volatile("s_waitcnt lgkmcnt(" #n ")" ::: "memory")
; #define PG8_BAR __builtin_amdgcn_s_barrier()
; #define PG8_SCHED __builtin_amdgcn_sched_barrier(0)
; template <class Epi, class Sched, bool ALIGN_EPI = false, bool SP2 = false>
; __device__ __forceinline__ void gemm_phase(PG8_LAS unsigned char* lds, const Gemm g, const Sched& S, const Epi& E) {
;     ...
;             PG8_WAIT_V(8); PG8_WAIT_L(0); PG8_BAR; PG8_MMA(1, 0, At, B0); PG8_MMA(1, 1, At, B1); PG8_BAR; PG8_SCHED;
;             PG8_LDB(B0, 1, 0); PG8_LDB(B1, 1, 1); PG8_SCHED; PG8_LDA(At, 1, 0); PG8_STAGE(PG8_SA(0, 1), a2 + hstep, voffA);
;             PG8_WAIT_V(8); PG8_WAIT_L(0); PG8_BAR; PG8_MMA(0, 0, At, B0); PG8_MMA(0, 1, At, B1); PG8_BAR; PG8_SCHED;
	s_setprio 1
	s_waitcnt lgkmcnt(0)
	v_mfma_f32_16x16x32_bf16 v[62:65], v[146:149], v[188:191], v[62:65]
	v_mfma_f32_16x16x32_bf16 v[58:61], v[164:167], v[188:191], v[58:61]
	v_mfma_f32_16x16x32_bf16 v[46:49], v[146:149], v[196:199], v[46:49]
	v_mfma_f32_16x16x32_bf16 v[42:45], v[164:167], v[196:199], v[42:45]
	v_mfma_f32_16x16x32_bf16 v[30:33], v[146:149], v[204:207], v[30:33]
	v_mfma_f32_16x16x32_bf16 v[26:29], v[164:167], v[204:207], v[26:29]
	v_mfma_f32_16x16x32_bf16 v[14:17], v[146:149], v[214:217], v[14:17]
	v_mfma_f32_16x16x32_bf16 v[10:13], v[164:167], v[214:217], v[10:13]
	v_mfma_f32_16x16x32_bf16 v[62:65], v[160:163], v[192:195], v[62:65]
	v_mfma_f32_16x16x32_bf16 v[58:61], v[168:171], v[192:195], v[58:61]
	v_mfma_f32_16x16x32_bf16 v[46:49], v[160:163], v[200:203], v[46:49]
	v_mfma_f32_16x16x32_bf16 v[42:45], v[168:171], v[200:203], v[42:45]
	v_mfma_f32_16x16x32_bf16 v[30:33], v[160:163], v[210:213], v[30:33]
	v_mfma_f32_16x16x32_bf16 v[26:29], v[168:171], v[210:213], v[26:29]
	v_mfma_f32_16x16x32_bf16 v[14:17], v[160:163], v[218:221], v[14:17]
	v_mfma_f32_16x16x32_bf16 v[10:13], v[168:171], v[218:221], v[10:13]
	s_setprio 0
	s_setprio 1
	v_mfma_f32_16x16x32_bf16 v[54:57], v[172:175], v[188:191], v[54:57]
	v_mfma_f32_16x16x32_bf16 v[50:53], v[180:183], v[188:191], v[50:53]
	v_mfma_f32_16x16x32_bf16 v[38:41], v[172:175], v[196:199], v[38:41]
	v_mfma_f32_16x16x32_bf16 v[34:37], v[180:183], v[196:199], v[34:37]
	v_mfma_f32_16x16x32_bf16 v[22:25], v[172:175], v[204:207], v[22:25]
	v_mfma_f32_16x16x32_bf16 v[18:21], v[180:183], v[204:207], v[18:21]
	v_mfma_f32_16x16x32_bf16 v[6:9], v[172:175], v[214:217], v[6:9]
	v_mfma_f32_16x16x32_bf16 v[2:5], v[180:183], v[214:217], v[2:5]
	v_mfma_f32_16x16x32_bf16 v[54:57], v[176:179], v[192:195], v[54:57]
	v_mfma_f32_16x16x32_bf16 v[50:53], v[184:187], v[192:195], v[50:53]
	v_mfma_f32_16x16x32_bf16 v[38:41], v[176:179], v[200:203], v[38:41]
	v_mfma_f32_16x16x32_bf16 v[34:37], v[184:187], v[200:203], v[34:37]
	v_mfma_f32_16x16x32_bf16 v[22:25], v[176:179], v[210:213], v[22:25]
	v_mfma_f32_16x16x32_bf16 v[18:21], v[184:187], v[210:213], v[18:21]
	v_mfma_f32_16x16x32_bf16 v[6:9], v[176:179], v[218:221], v[6:9]
	v_mfma_f32_16x16x32_bf16 v[2:5], v[184:187], v[218:221], v[2:5]
	s_setprio 0
	s_barrier
	ds_read_b128 v[146:149], v157
	ds_read_b128 v[160:163], v157 offset:1024
	ds_read_b128 v[164:167], v157 offset:2048
	ds_read_b128 v[168:171], v157 offset:3072
	ds_read_b128 v[172:175], v158
	ds_read_b128 v[176:179], v158 offset:1024
	ds_read_b128 v[180:183], v158 offset:2048
	ds_read_b128 v[184:187], v158 offset:3072
	s_add_u32 s0, s28, 0x40000
	s_addc_u32 s1, s29, 0
	s_mov_b32 m0, s36
	v_lshl_add_u64 v[230:231], s[0:1], 0, v[130:131]
	ds_read_b128 v[188:191], v155 offset:32768
	ds_read_b128 v[192:195], v155 offset:33792
	ds_read_b128 v[196:199], v155 offset:34816
	ds_read_b128 v[200:203], v155 offset:35840
	ds_read_b128 v[204:207], v155 offset:36864
	ds_read_b128 v[210:213], v155 offset:37888
	ds_read_b128 v[214:217], v155 offset:38912
	ds_read_b128 v[218:221], v155 offset:39936
	global_load_lds_dwordx4 v[230:231], off
	v_lshl_add_u64 v[230:231], s[0:1], 0, v[134:135]
	s_mov_b32 m0, s37
	s_nop 0
	global_load_lds_dwordx4 v[230:231], off
	s_waitcnt vmcnt(8)
	s_waitcnt lgkmcnt(0)
	s_barrier
	s_setprio 1
	s_waitcnt lgkmcnt(0)
	v_mfma_f32_16x16x32_bf16 v[126:129], v[146:149], v[188:191], v[126:129]
	v_mfma_f32_16x16x32_bf16 v[122:125], v[164:167], v[188:191], v[122:125]
	v_mfma_f32_16x16x32_bf16 v[110:113], v[146:149], v[196:199], v[110:113]
	v_mfma_f32_16x16x32_bf16 v[106:109], v[164:167], v[196:199], v[106:109]
	v_mfma_f32_16x16x32_bf16 v[94:97], v[146:149], v[204:207], v[94:97]
	v_mfma_f32_16x16x32_bf16 v[90:93], v[164:167], v[204:207], v[90:93]
	v_mfma_f32_16x16x32_bf16 v[78:81], v[146:149], v[214:217], v[78:81]
	v_mfma_f32_16x16x32_bf16 v[74:77], v[164:167], v[214:217], v[74:77]
	v_mfma_f32_16x16x32_bf16 v[126:129], v[160:163], v[192:195], v[126:129]
	v_mfma_f32_16x16x32_bf16 v[122:125], v[168:171], v[192:195], v[122:125]
	v_mfma_f32_16x16x32_bf16 v[110:113], v[160:163], v[200:203], v[110:113]
	v_mfma_f32_16x16x32_bf16 v[106:109], v[168:171], v[200:203], v[106:109]
	v_mfma_f32_16x16x32_bf16 v[94:97], v[160:163], v[210:213], v[94:97]
	v_mfma_f32_16x16x32_bf16 v[90:93], v[168:171], v[210:213], v[90:93]
	v_mfma_f32_16x16x32_bf16 v[78:81], v[160:163], v[218:221], v[78:81]
	v_mfma_f32_16x16x32_bf16 v[74:77], v[168:171], v[218:221], v[74:77]
	s_setprio 0
	s_setprio 1
	v_mfma_f32_16x16x32_bf16 v[118:121], v[172:175], v[188:191], v[118:121]
	v_mfma_f32_16x16x32_bf16 v[114:117], v[180:183], v[188:191], v[114:117]
	v_mfma_f32_16x16x32_bf16 v[102:105], v[172:175], v[196:199], v[102:105]
	v_mfma_f32_16x16x32_bf16 v[98:101], v[180:183], v[196:199], v[98:101]
	v_mfma_f32_16x16x32_bf16 v[86:89], v[172:175], v[204:207], v[86:89]
	v_mfma_f32_16x16x32_bf16 v[82:85], v[180:183], v[204:207], v[82:85]
	v_mfma_f32_16x16x32_bf16 v[70:73], v[172:175], v[214:217], v[70:73]
	v_mfma_f32_16x16x32_bf16 v[66:69], v[180:183], v[214:217], v[66:69]
	v_mfma_f32_16x16x32_bf16 v[118:121], v[176:179], v[192:195], v[118:121]
	v_mfma_f32_16x16x32_bf16 v[114:117], v[184:187], v[192:195], v[114:117]
	v_mfma_f32_16x16x32_bf16 v[102:105], v[176:179], v[200:203], v[102:105]
	v_mfma_f32_16x16x32_bf16 v[98:101], v[184:187], v[200:203], v[98:101]
	v_mfma_f32_16x16x32_bf16 v[86:89], v[176:179], v[210:213], v[86:89]
	v_mfma_f32_16x16x32_bf16 v[82:85], v[184:187], v[210:213], v[82:85]
	v_mfma_f32_16x16x32_bf16 v[70:73], v[176:179], v[218:221], v[70:73]
	v_mfma_f32_16x16x32_bf16 v[66:69], v[184:187], v[218:221], v[66:69]
	s_setprio 0
	s_barrier
; #define PG8_STAGE(bufoff, gbase, voff) do { _Pragma("unroll") for (int _i = 0; _i < 2; ++_i) \
;         __builtin_amdgcn_global_load_lds((const unsigned*)((const char*)(gbase) + (voff)[_i]), (PG8_LAS unsigned*)(lds + (bufoff) + ldsw + _i * 8192), 16, 0, 0); } while (0)
; #define PG8_LDA(dst, b, h) do { _Pragma("unroll") for (int m = 0; m < 4; ++m) _Pragma("unroll") for (int k = 0; k < 2; ++k) dst[m][k] = *(const PG8_LAS bf16x8*)(lds + PG8_SA(b, h) + aoff + m * 2048 + k * 1024); } while (0)
; #define PG8_MMA(ai, bj, At, Bt) do { __builtin_amdgcn_s_setprio(1); _Pragma("unroll") for (int m = 0; m < 4; ++m) _Pragma("unroll") for (int n = 0; n < 2; ++n) _Pragma("unroll") for (int k = 0; k < 2; ++k) \
;         acc[ai][bj][m][n] = __builtin_amdgcn_mfma_f32_16x16x32_bf16(Bt[n][k], At[m][k], acc[ai][bj][m][n], 0, 0, 0); __builtin_amdgcn_s_setprio(0); } while (0)
; #define PG8_WAIT_V(n) asm volatile("s_waitcnt vmcnt(" #n ")" ::: "memory")
; #define PG8_WAIT_L(n) asm volatile("s_waitcnt lgkmcnt(" #n ")" ::: "memory")
; #define PG8_BAR __builtin_amdgcn_s_barrier()
; #define PG8_SCHED __builtin_amdgcn_sched_barrier(0)
; template <class Epi, class Sched, bool ALIGN_EPI = false, bool SP2 = false>
; __device__ __forceinline__ void gemm_phase(PG8_LAS unsigned char* lds, const Gemm g, const Sched& S, const Epi& E) {
;     ...
;             PG8_LDA(At, 1, 1); PG8_STAGE(PG8_SB(1, 0), b3, voffB); PG8_STAGE(PG8_SB(1, 1), b3 + hstep, voffB); PG8_STAGE(PG8_SA(1, 0), a3, voffA);
;             PG8_WAIT_V(8); PG8_WAIT_L(0); PG8_BAR; PG8_MMA(1, 0, At, B0); PG8_MMA(1, 1, At, B1); PG8_BAR; PG8_SCHED;
;     ...
;         if constexpr (ALIGN_EPI) { if (wr == 0) PG8_BAR; }
	s_add_i32 s0, s45, s31
	v_lshl_add_u64 v[222:223], v[222:223], 0, s[10:11]
	s_mov_b32 m0, s0
	ds_read_b128 v[188:191], v155 offset:49152
	ds_read_b128 v[192:195], v155 offset:50176
	ds_read_b128 v[196:199], v155 offset:51200
	ds_read_b128 v[200:203], v155 offset:52224
	ds_read_b128 v[204:207], v155 offset:53248
	ds_read_b128 v[210:213], v155 offset:54272
	ds_read_b128 v[214:217], v155 offset:55296
	ds_read_b128 v[218:221], v155 offset:56320
	global_load_lds_dwordx4 v[222:223], off
	s_add_i32 m0, s0, 0x2000
	s_add_u32 s0, s26, 0x10080
	v_lshl_add_u64 v[222:223], v[224:225], 0, s[10:11]
	s_addc_u32 s1, s27, 0
	s_add_i32 s26, s46, s31
	global_load_lds_dwordx4 v[222:223], off
	v_lshl_add_u64 v[222:223], s[0:1], 0, v[132:133]
	s_mov_b32 m0, s26
	s_nop 0
	global_load_lds_dwordx4 v[222:223], off
	v_lshl_add_u64 v[222:223], s[0:1], 0, v[136:137]
	s_add_i32 m0, s26, 0x2000
	s_nop 0
	global_load_lds_dwordx4 v[222:223], off
	v_lshl_add_u64 v[222:223], v[226:227], 0, s[10:11]
	s_mov_b32 m0, s38
	s_nop 0
	global_load_lds_dwordx4 v[222:223], off
	v_lshl_add_u64 v[222:223], v[228:229], 0, s[10:11]
	s_mov_b32 m0, s39
	s_nop 0
	global_load_lds_dwordx4 v[222:223], off
	s_waitcnt vmcnt(8)
	s_waitcnt lgkmcnt(0)
	s_barrier
	s_setprio 1
	s_waitcnt lgkmcnt(0)
	v_mfma_f32_16x16x32_bf16 v[62:65], v[146:149], v[188:191], v[62:65]
	v_mfma_f32_16x16x32_bf16 v[58:61], v[164:167], v[188:191], v[58:61]
	v_mfma_f32_16x16x32_bf16 v[46:49], v[146:149], v[196:199], v[46:49]
	v_mfma_f32_16x16x32_bf16 v[42:45], v[164:167], v[196:199], v[42:45]
	v_mfma_f32_16x16x32_bf16 v[30:33], v[146:149], v[204:207], v[30:33]
	v_mfma_f32_16x16x32_bf16 v[26:29], v[164:167], v[204:207], v[26:29]
	v_mfma_f32_16x16x32_bf16 v[14:17], v[146:149], v[214:217], v[14:17]
	v_mfma_f32_16x16x32_bf16 v[10:13], v[164:167], v[214:217], v[10:13]
	v_mfma_f32_16x16x32_bf16 v[62:65], v[160:163], v[192:195], v[62:65]
	v_mfma_f32_16x16x32_bf16 v[58:61], v[168:171], v[192:195], v[58:61]
	v_mfma_f32_16x16x32_bf16 v[46:49], v[160:163], v[200:203], v[46:49]
	v_mfma_f32_16x16x32_bf16 v[42:45], v[168:171], v[200:203], v[42:45]
	v_mfma_f32_16x16x32_bf16 v[30:33], v[160:163], v[210:213], v[30:33]
	v_mfma_f32_16x16x32_bf16 v[26:29], v[168:171], v[210:213], v[26:29]
	v_mfma_f32_16x16x32_bf16 v[14:17], v[160:163], v[218:221], v[14:17]
	v_mfma_f32_16x16x32_bf16 v[10:13], v[168:171], v[218:221], v[10:13]
	s_setprio 0
	s_setprio 1
	v_mfma_f32_16x16x32_bf16 v[54:57], v[172:175], v[188:191], v[54:57]
	v_mfma_f32_16x16x32_bf16 v[50:53], v[180:183], v[188:191], v[50:53]
	v_mfma_f32_16x16x32_bf16 v[38:41], v[172:175], v[196:199], v[38:41]
	v_mfma_f32_16x16x32_bf16 v[34:37], v[180:183], v[196:199], v[34:37]
	v_mfma_f32_16x16x32_bf16 v[22:25], v[172:175], v[204:207], v[22:25]
	v_mfma_f32_16x16x32_bf16 v[18:21], v[180:183], v[204:207], v[18:21]
	v_mfma_f32_16x16x32_bf16 v[6:9], v[172:175], v[214:217], v[6:9]
	v_mfma_f32_16x16x32_bf16 v[2:5], v[180:183], v[214:217], v[2:5]
	v_mfma_f32_16x16x32_bf16 v[54:57], v[176:179], v[192:195], v[54:57]
	v_mfma_f32_16x16x32_bf16 v[50:53], v[184:187], v[192:195], v[50:53]
	v_mfma_f32_16x16x32_bf16 v[38:41], v[176:179], v[200:203], v[38:41]
	v_mfma_f32_16x16x32_bf16 v[34:37], v[184:187], v[200:203], v[34:37]
	v_mfma_f32_16x16x32_bf16 v[22:25], v[176:179], v[210:213], v[22:25]
	v_mfma_f32_16x16x32_bf16 v[18:21], v[184:187], v[210:213], v[18:21]
	v_mfma_f32_16x16x32_bf16 v[6:9], v[176:179], v[218:221], v[6:9]
	v_mfma_f32_16x16x32_bf16 v[2:5], v[184:187], v[218:221], v[2:5]
	s_setprio 0
	s_barrier
	s_add_i32 s54, s54, 2
	s_add_u32 s4, s4, 0x100
	s_addc_u32 s5, s5, 0
	s_add_u32 s52, s52, 0x100
	s_addc_u32 s53, s53, 0
	s_cmp_gt_u32 s54, 13
	s_cbranch_scc0 .LBB0_1380
	s_and_b64 vcc, exec, s[12:13]
	s_cbranch_vccz .LBB0_1383
	s_barrier

; __device__ __forceinline__ unsigned cvt_pk_bf16(float lo, float hi) { unsigned r; asm volatile("v_cvt_pk_bf16_f32 %0, %1, %2" : "=v"(r) : "v"(lo), "v"(hi)); return r; }
;     __device__ __forceinline__ void operator()(const f32x4 (&acc)[2][2][4][2], const Unit& u, int wr, int wc, int fr, int fq) const {
;     ...
;             for (int m = 0; m < 4; ++m) { const int r = row0 + ai * HALF + m * 16;
;                 float rstd;
;                 if (u.idx < UP_TAB_ROUNDS) rstd = tab[u.idx * BM + ai * HALF + wr * 64 + m * 16 + fr];
;                 else { const f32x4 p = *(const f32x4*)(stats + (size_t)r * 16 + 4 * fq); float s = (p[0] + p[1]) + (p[2] + p[3]);
;                     s += __shfl_xor(s, 16); s += __shfl_xor(s, 32); rstd = __builtin_amdgcn_rsqf(s * (1.0f / 1024.0f) + RMS_EPS); }
;                 bf16_t* rowp = H + (size_t)r * 4096 + col0;
; #pragma unroll
;                 for (int bj = 0; bj < 2; ++bj) { f32x4 v0 = acc[ai][bj][m][0] * rstd, v1 = acc[ai][bj][m][1] * rstd;
; #pragma unroll
;                     for (int e = 0; e < 4; ++e) { const float a = fmaxf(v0[e], 0.f), b = fmaxf(v1[e], 0.f); v0[e] = a * a; v1[e] = b * b; }
;                     u32x4 w; w.x = cvt_pk_bf16(v0[0], v0[1]); w.y = cvt_pk_bf16(v0[2], v0[3]); w.z = cvt_pk_bf16(v1[0], v1[1]); w.w = cvt_pk_bf16(v1[2], v1[3]);
;                     __builtin_nontemporal_store(w, (u32x4*)(rowp + bj * HALF)); } }
.LBB0_1387:
	s_waitcnt lgkmcnt(0)
	v_pk_mul_f32 v[122:123], v[122:123], v[150:151] op_sel_hi:[1,0]
	v_pk_mul_f32 v[126:127], v[126:127], v[150:151] op_sel_hi:[1,0]
	v_pk_mul_f32 v[124:125], v[124:125], v[150:151] op_sel_hi:[1,0]
	v_max_f32_e32 v122, 0, v122
	v_mov_b32_e32 v148, v152
	v_lshlrev_b64 v[162:163], 7, v[146:147]
	v_pk_mul_f32 v[128:129], v[128:129], v[150:151] op_sel_hi:[1,0]
	v_mul_f32_e32 v147, v122, v122
	v_max_f32_e32 v122, 0, v127
	v_max_f32_e32 v123, 0, v123
	v_max_f32_e32 v124, 0, v124
	v_ashrrev_i32_e32 v149, 31, v148
	v_lshl_add_u64 v[162:163], s[56:57], 0, v[162:163]
	v_max_f32_e32 v126, 0, v126
	v_mul_f32_e32 v122, v122, v122
	v_mul_f32_e32 v127, v123, v123
	v_max_f32_e32 v123, 0, v128
	v_mul_f32_e32 v128, v124, v124
	v_max_f32_e32 v124, 0, v129
	v_max_f32_e32 v125, 0, v125
	v_pk_mul_f32 v[116:117], v[116:117], v[150:151] op_sel_hi:[1,0]
	v_pk_mul_f32 v[114:115], v[114:115], v[150:151] op_sel_hi:[1,0]
	v_lshl_add_u64 v[162:163], v[148:149], 1, v[162:163]
	v_mul_f32_e32 v126, v126, v126
	v_mul_f32_e32 v123, v123, v123
	v_mul_f32_e32 v124, v124, v124
	v_mul_f32_e32 v125, v125, v125
	v_cvt_pk_bf16_f32 v122, v126, v122
	v_pk_mul_f32 v[120:121], v[120:121], v[150:151] op_sel_hi:[1,0]
	v_pk_mul_f32 v[118:119], v[118:119], v[150:151] op_sel_hi:[1,0]
	v_max_f32_e32 v114, 0, v114
	v_max_f32_e32 v115, 0, v115
	v_max_f32_e32 v116, 0, v116
	v_cvt_pk_bf16_f32 v123, v123, v124
	v_cvt_pk_bf16_f32 v124, v147, v127
	v_cvt_pk_bf16_f32 v125, v128, v125
	global_store_dwordx4 v[162:163], v[122:125], off nt
	v_max_f32_e32 v118, 0, v118
	v_max_f32_e32 v117, 0, v117
	v_mul_f32_e32 v122, v114, v114
	v_max_f32_e32 v114, 0, v119
	v_mul_f32_e32 v119, v115, v115
	v_max_f32_e32 v115, 0, v120
	v_mul_f32_e32 v120, v116, v116
	v_max_f32_e32 v116, 0, v121
	v_mul_f32_e32 v114, v114, v114
	v_mul_f32_e32 v115, v115, v115
	v_mul_f32_e32 v116, v116, v116
	v_mul_f32_e32 v118, v118, v118
	v_mul_f32_e32 v117, v117, v117
	v_cvt_pk_bf16_f32 v114, v118, v114
	v_cvt_pk_bf16_f32 v115, v115, v116
	v_cvt_pk_bf16_f32 v116, v122, v119
	v_cvt_pk_bf16_f32 v117, v120, v117
	global_store_dwordx4 v[162:163], v[114:117], off offset:64 nt
	s_mov_b64 s[22:23], -1
	s_andn2_b64 vcc, exec, s[24:25]
	v_or_b32_e32 v116, 16, v146
	v_cndmask_b32_e64 v114, 0, 1, s[24:25]
	v_cmp_ne_u32_e64 s[4:5], 1, v114
	v_ashrrev_i32_e32 v117, 31, v116
	s_cbranch_vccnz .LBB0_1389
	v_lshlrev_b64 v[114:115], 6, v[116:117]
	v_lshl_add_u64 v[114:115], v[138:139], 0, v[114:115]
	global_load_dwordx4 v[118:121], v[114:115], off
	v_and_b32_e32 v115, 64, v159
	v_xor_b32_e32 v114, 16, v159
	v_add_u32_e32 v122, 64, v115
	v_cmp_lt_i32_e32 vcc, v114, v122
	s_mov_b64 s[22:23], 0
	s_waitcnt vmcnt(0)
	v_mov_b32_e32 v115, v120
	v_cndmask_b32_e32 v114, v159, v114, vcc
	v_lshlrev_b32_e32 v123, 2, v114
	v_mov_b32_e32 v114, v119
	v_mov_b32_e32 v119, v121
	v_pk_add_f32 v[114:115], v[114:115], v[118:119]
	v_xor_b32_e32 v118, 32, v159
	v_add_f32_e32 v114, v114, v115
	ds_bpermute_b32 v115, v123, v114
	v_cmp_lt_i32_e32 vcc, v118, v122
	s_waitcnt lgkmcnt(0)
	v_add_f32_e32 v114, v114, v115
	v_cndmask_b32_e32 v118, v159, v118, vcc
	v_lshlrev_b32_e32 v115, 2, v118
	ds_bpermute_b32 v115, v115, v114
	s_waitcnt lgkmcnt(0)
	v_add_f32_e32 v114, v114, v115
	v_fmamk_f32 v114, v114, 0x3a800000, v156
	v_rsq_f32_e32 v114, v114

; __device__ __forceinline__ unsigned cvt_pk_bf16(float lo, float hi) { unsigned r; asm volatile("v_cvt_pk_bf16_f32 %0, %1, %2" : "=v"(r) : "v"(lo), "v"(hi)); return r; }
;     __device__ __forceinline__ void operator()(const f32x4 (&acc)[2][2][4][2], const Unit& u, int wr, int wc, int fr, int fq) const {
;     ...
;             for (int m = 0; m < 4; ++m) { const int r = row0 + ai * HALF + m * 16;
;                 float rstd;
;                 if (u.idx < UP_TAB_ROUNDS) rstd = tab[u.idx * BM + ai * HALF + wr * 64 + m * 16 + fr];
;                 else { const f32x4 p = *(const f32x4*)(stats + (size_t)r * 16 + 4 * fq); float s = (p[0] + p[1]) + (p[2] + p[3]);
;                     s += __shfl_xor(s, 16); s += __shfl_xor(s, 32); rstd = __builtin_amdgcn_rsqf(s * (1.0f / 1024.0f) + RMS_EPS); }
;                 bf16_t* rowp = H + (size_t)r * 4096 + col0;
; #pragma unroll
;                 for (int bj = 0; bj < 2; ++bj) { f32x4 v0 = acc[ai][bj][m][0] * rstd, v1 = acc[ai][bj][m][1] * rstd;
; #pragma unroll
;                     for (int e = 0; e < 4; ++e) { const float a = fmaxf(v0[e], 0.f), b = fmaxf(v1[e], 0.f); v0[e] = a * a; v1[e] = b * b; }
;                     u32x4 w; w.x = cvt_pk_bf16(v0[0], v0[1]); w.y = cvt_pk_bf16(v0[2], v0[3]); w.z = cvt_pk_bf16(v1[0], v1[1]); w.w = cvt_pk_bf16(v1[2], v1[3]);
;                     __builtin_nontemporal_store(w, (u32x4*)(rowp + bj * HALF)); } }
.LBB0_1391:
	s_waitcnt lgkmcnt(0)
	v_pk_mul_f32 v[106:107], v[106:107], v[114:115] op_sel_hi:[1,0]
	v_pk_mul_f32 v[110:111], v[110:111], v[114:115] op_sel_hi:[1,0]
	v_pk_mul_f32 v[108:109], v[108:109], v[114:115] op_sel_hi:[1,0]
	v_max_f32_e32 v106, 0, v106
	v_lshlrev_b64 v[116:117], 7, v[116:117]
	v_pk_mul_f32 v[112:113], v[112:113], v[114:115] op_sel_hi:[1,0]
	v_mul_f32_e32 v115, v106, v106
	v_max_f32_e32 v106, 0, v111
	v_max_f32_e32 v107, 0, v107
	v_max_f32_e32 v108, 0, v108
	v_lshl_add_u64 v[116:117], s[56:57], 0, v[116:117]
	v_max_f32_e32 v110, 0, v110
	v_mul_f32_e32 v106, v106, v106
	v_mul_f32_e32 v111, v107, v107
	v_max_f32_e32 v107, 0, v112
	v_mul_f32_e32 v112, v108, v108
	v_max_f32_e32 v108, 0, v113
	v_max_f32_e32 v109, 0, v109
	v_pk_mul_f32 v[100:101], v[100:101], v[114:115] op_sel_hi:[1,0]
	v_pk_mul_f32 v[98:99], v[98:99], v[114:115] op_sel_hi:[1,0]
	v_lshl_add_u64 v[116:117], v[148:149], 1, v[116:117]
	v_mul_f32_e32 v110, v110, v110
	v_mul_f32_e32 v107, v107, v107
	v_mul_f32_e32 v108, v108, v108
	v_mul_f32_e32 v109, v109, v109
	v_cvt_pk_bf16_f32 v106, v110, v106
	v_pk_mul_f32 v[104:105], v[104:105], v[114:115] op_sel_hi:[1,0]
	v_pk_mul_f32 v[102:103], v[102:103], v[114:115] op_sel_hi:[1,0]
	v_max_f32_e32 v98, 0, v98
	v_max_f32_e32 v99, 0, v99
	v_max_f32_e32 v100, 0, v100
	v_cvt_pk_bf16_f32 v107, v107, v108
	v_cvt_pk_bf16_f32 v108, v115, v111
	v_cvt_pk_bf16_f32 v109, v112, v109
	global_store_dwordx4 v[116:117], v[106:109], off nt
	v_max_f32_e32 v102, 0, v102
	v_max_f32_e32 v101, 0, v101
	v_mul_f32_e32 v106, v98, v98
	v_max_f32_e32 v98, 0, v103
	v_mul_f32_e32 v103, v99, v99
	v_max_f32_e32 v99, 0, v104
	v_mul_f32_e32 v104, v100, v100
	v_max_f32_e32 v100, 0, v105
	v_mul_f32_e32 v98, v98, v98
	v_mul_f32_e32 v99, v99, v99
	v_mul_f32_e32 v100, v100, v100
	v_mul_f32_e32 v102, v102, v102
	v_mul_f32_e32 v101, v101, v101
	v_cvt_pk_bf16_f32 v98, v102, v98
	v_cvt_pk_bf16_f32 v99, v99, v100
	v_cvt_pk_bf16_f32 v100, v106, v103
	v_cvt_pk_bf16_f32 v101, v104, v101
	global_store_dwordx4 v[116:117], v[98:101], off offset:64 nt
	s_mov_b64 s[22:23], -1
	s_and_b64 vcc, exec, s[4:5]
	v_or_b32_e32 v100, 32, v146
	v_ashrrev_i32_e32 v101, 31, v100
	s_cbranch_vccnz .LBB0_1393
	v_lshlrev_b64 v[98:99], 6, v[100:101]
	v_lshl_add_u64 v[98:99], v[138:139], 0, v[98:99]
	global_load_dwordx4 v[102:105], v[98:99], off
	v_and_b32_e32 v99, 64, v159
	v_xor_b32_e32 v98, 16, v159
	v_add_u32_e32 v106, 64, v99
	v_cmp_lt_i32_e32 vcc, v98, v106
	s_mov_b64 s[22:23], 0
	s_waitcnt vmcnt(0)
	v_mov_b32_e32 v99, v104
	v_cndmask_b32_e32 v98, v159, v98, vcc
	v_lshlrev_b32_e32 v107, 2, v98
	v_mov_b32_e32 v98, v103
	v_mov_b32_e32 v103, v105
	v_pk_add_f32 v[98:99], v[98:99], v[102:103]
	v_xor_b32_e32 v102, 32, v159
	v_add_f32_e32 v98, v98, v99
	ds_bpermute_b32 v99, v107, v98
	v_cmp_lt_i32_e32 vcc, v102, v106
	s_waitcnt lgkmcnt(0)
	v_add_f32_e32 v98, v98, v99
	v_cndmask_b32_e32 v102, v159, v102, vcc
	v_lshlrev_b32_e32 v99, 2, v102
	ds_bpermute_b32 v99, v99, v98
	s_waitcnt lgkmcnt(0)
	v_add_f32_e32 v98, v98, v99
	v_fmamk_f32 v98, v98, 0x3a800000, v156
	v_rsq_f32_e32 v98, v98

; __device__ __forceinline__ unsigned cvt_pk_bf16(float lo, float hi) { unsigned r; asm volatile("v_cvt_pk_bf16_f32 %0, %1, %2" : "=v"(r) : "v"(lo), "v"(hi)); return r; }
;     __device__ __forceinline__ void operator()(const f32x4 (&acc)[2][2][4][2], const Unit& u, int wr, int wc, int fr, int fq) const {
;     ...
;             for (int m = 0; m < 4; ++m) { const int r = row0 + ai * HALF + m * 16;
;                 float rstd;
;                 if (u.idx < UP_TAB_ROUNDS) rstd = tab[u.idx * BM + ai * HALF + wr * 64 + m * 16 + fr];
;                 else { const f32x4 p = *(const f32x4*)(stats + (size_t)r * 16 + 4 * fq); float s = (p[0] + p[1]) + (p[2] + p[3]);
;                     s += __shfl_xor(s, 16); s += __shfl_xor(s, 32); rstd = __builtin_amdgcn_rsqf(s * (1.0f / 1024.0f) + RMS_EPS); }
;                 bf16_t* rowp = H + (size_t)r * 4096 + col0;
; #pragma unroll
;                 for (int bj = 0; bj < 2; ++bj) { f32x4 v0 = acc[ai][bj][m][0] * rstd, v1 = acc[ai][bj][m][1] * rstd;
; #pragma unroll
;                     for (int e = 0; e < 4; ++e) { const float a = fmaxf(v0[e], 0.f), b = fmaxf(v1[e], 0.f); v0[e] = a * a; v1[e] = b * b; }
;                     u32x4 w; w.x = cvt_pk_bf16(v0[0], v0[1]); w.y = cvt_pk_bf16(v0[2], v0[3]); w.z = cvt_pk_bf16(v1[0], v1[1]); w.w = cvt_pk_bf16(v1[2], v1[3]);
;                     __builtin_nontemporal_store(w, (u32x4*)(rowp + bj * HALF)); } }
.LBB0_1395:
	s_waitcnt lgkmcnt(0)
	v_pk_mul_f32 v[90:91], v[90:91], v[98:99] op_sel_hi:[1,0]
	v_pk_mul_f32 v[94:95], v[94:95], v[98:99] op_sel_hi:[1,0]
	v_pk_mul_f32 v[92:93], v[92:93], v[98:99] op_sel_hi:[1,0]
	v_max_f32_e32 v90, 0, v90
	v_lshlrev_b64 v[100:101], 7, v[100:101]
	v_pk_mul_f32 v[96:97], v[96:97], v[98:99] op_sel_hi:[1,0]
	v_mul_f32_e32 v99, v90, v90
	v_max_f32_e32 v90, 0, v95
	v_max_f32_e32 v91, 0, v91
	v_max_f32_e32 v92, 0, v92
	v_lshl_add_u64 v[100:101], s[56:57], 0, v[100:101]
	v_max_f32_e32 v94, 0, v94
	v_mul_f32_e32 v90, v90, v90
	v_mul_f32_e32 v95, v91, v91
	v_max_f32_e32 v91, 0, v96
	v_mul_f32_e32 v96, v92, v92
	v_max_f32_e32 v92, 0, v97
	v_max_f32_e32 v93, 0, v93
	v_pk_mul_f32 v[84:85], v[84:85], v[98:99] op_sel_hi:[1,0]
	v_pk_mul_f32 v[82:83], v[82:83], v[98:99] op_sel_hi:[1,0]
	v_lshl_add_u64 v[100:101], v[148:149], 1, v[100:101]
	v_mul_f32_e32 v94, v94, v94
	v_mul_f32_e32 v91, v91, v91
	v_mul_f32_e32 v92, v92, v92
	v_mul_f32_e32 v93, v93, v93
	v_cvt_pk_bf16_f32 v90, v94, v90
	v_pk_mul_f32 v[88:89], v[88:89], v[98:99] op_sel_hi:[1,0]
	v_pk_mul_f32 v[86:87], v[86:87], v[98:99] op_sel_hi:[1,0]
	v_max_f32_e32 v82, 0, v82
	v_max_f32_e32 v83, 0, v83
	v_max_f32_e32 v84, 0, v84
	v_cvt_pk_bf16_f32 v91, v91, v92
	v_cvt_pk_bf16_f32 v92, v99, v95
	v_cvt_pk_bf16_f32 v93, v96, v93
	global_store_dwordx4 v[100:101], v[90:93], off nt
	v_max_f32_e32 v86, 0, v86
	v_max_f32_e32 v85, 0, v85
	v_mul_f32_e32 v90, v82, v82
	v_max_f32_e32 v82, 0, v87
	v_mul_f32_e32 v87, v83, v83
	v_max_f32_e32 v83, 0, v88
	v_mul_f32_e32 v88, v84, v84
	v_max_f32_e32 v84, 0, v89
	v_mul_f32_e32 v82, v82, v82
	v_mul_f32_e32 v83, v83, v83
	v_mul_f32_e32 v84, v84, v84
	v_mul_f32_e32 v86, v86, v86
	v_mul_f32_e32 v85, v85, v85
	v_cvt_pk_bf16_f32 v82, v86, v82
	v_cvt_pk_bf16_f32 v83, v83, v84
	v_cvt_pk_bf16_f32 v84, v90, v87
	v_cvt_pk_bf16_f32 v85, v88, v85
	global_store_dwordx4 v[100:101], v[82:85], off offset:64 nt
	s_mov_b64 s[22:23], -1
	s_and_b64 vcc, exec, s[4:5]
	v_or_b32_e32 v84, 48, v146
	v_ashrrev_i32_e32 v85, 31, v84
	s_cbranch_vccnz .LBB0_1397
	v_lshlrev_b64 v[82:83], 6, v[84:85]
	v_lshl_add_u64 v[82:83], v[138:139], 0, v[82:83]
	global_load_dwordx4 v[86:89], v[82:83], off
	v_and_b32_e32 v83, 64, v159
	v_xor_b32_e32 v82, 16, v159
	v_add_u32_e32 v90, 64, v83
	v_cmp_lt_i32_e32 vcc, v82, v90
	s_mov_b64 s[22:23], 0
	s_waitcnt vmcnt(0)
	v_mov_b32_e32 v83, v88
	v_cndmask_b32_e32 v82, v159, v82, vcc
	v_lshlrev_b32_e32 v91, 2, v82
	v_mov_b32_e32 v82, v87
	v_mov_b32_e32 v87, v89
	v_pk_add_f32 v[82:83], v[82:83], v[86:87]
	v_xor_b32_e32 v86, 32, v159
	v_add_f32_e32 v82, v82, v83
	ds_bpermute_b32 v83, v91, v82
	v_cmp_lt_i32_e32 vcc, v86, v90
	s_waitcnt lgkmcnt(0)
	v_add_f32_e32 v82, v82, v83
	v_cndmask_b32_e32 v86, v159, v86, vcc
	v_lshlrev_b32_e32 v83, 2, v86
	ds_bpermute_b32 v83, v83, v82
	s_waitcnt lgkmcnt(0)
	v_add_f32_e32 v82, v82, v83
	v_fmamk_f32 v82, v82, 0x3a800000, v156
	v_rsq_f32_e32 v82, v82

; __device__ __forceinline__ unsigned cvt_pk_bf16(float lo, float hi) { unsigned r; asm volatile("v_cvt_pk_bf16_f32 %0, %1, %2" : "=v"(r) : "v"(lo), "v"(hi)); return r; }
;     __device__ __forceinline__ void operator()(const f32x4 (&acc)[2][2][4][2], const Unit& u, int wr, int wc, int fr, int fq) const {
;     ...
;             for (int m = 0; m < 4; ++m) { const int r = row0 + ai * HALF + m * 16;
;                 float rstd;
;                 if (u.idx < UP_TAB_ROUNDS) rstd = tab[u.idx * BM + ai * HALF + wr * 64 + m * 16 + fr];
;                 else { const f32x4 p = *(const f32x4*)(stats + (size_t)r * 16 + 4 * fq); float s = (p[0] + p[1]) + (p[2] + p[3]);
;                     s += __shfl_xor(s, 16); s += __shfl_xor(s, 32); rstd = __builtin_amdgcn_rsqf(s * (1.0f / 1024.0f) + RMS_EPS); }
;                 bf16_t* rowp = H + (size_t)r * 4096 + col0;
; #pragma unroll
;                 for (int bj = 0; bj < 2; ++bj) { f32x4 v0 = acc[ai][bj][m][0] * rstd, v1 = acc[ai][bj][m][1] * rstd;
; #pragma unroll
;                     for (int e = 0; e < 4; ++e) { const float a = fmaxf(v0[e], 0.f), b = fmaxf(v1[e], 0.f); v0[e] = a * a; v1[e] = b * b; }
;                     u32x4 w; w.x = cvt_pk_bf16(v0[0], v0[1]); w.y = cvt_pk_bf16(v0[2], v0[3]); w.z = cvt_pk_bf16(v1[0], v1[1]); w.w = cvt_pk_bf16(v1[2], v1[3]);
;                     __builtin_nontemporal_store(w, (u32x4*)(rowp + bj * HALF)); } }
.LBB0_1399:
	s_waitcnt lgkmcnt(0)
	v_pk_mul_f32 v[74:75], v[74:75], v[82:83] op_sel_hi:[1,0]
	v_pk_mul_f32 v[78:79], v[78:79], v[82:83] op_sel_hi:[1,0]
	v_pk_mul_f32 v[76:77], v[76:77], v[82:83] op_sel_hi:[1,0]
	v_max_f32_e32 v74, 0, v74
	v_lshlrev_b64 v[84:85], 7, v[84:85]
	v_pk_mul_f32 v[80:81], v[80:81], v[82:83] op_sel_hi:[1,0]
	v_mul_f32_e32 v83, v74, v74
	v_max_f32_e32 v74, 0, v79
	v_max_f32_e32 v75, 0, v75
	v_max_f32_e32 v76, 0, v76
	v_lshl_add_u64 v[84:85], s[56:57], 0, v[84:85]
	v_max_f32_e32 v78, 0, v78
	v_mul_f32_e32 v74, v74, v74
	v_mul_f32_e32 v79, v75, v75
	v_max_f32_e32 v75, 0, v80
	v_mul_f32_e32 v80, v76, v76
	v_max_f32_e32 v76, 0, v81
	v_max_f32_e32 v77, 0, v77
	v_pk_mul_f32 v[68:69], v[68:69], v[82:83] op_sel_hi:[1,0]
	v_pk_mul_f32 v[66:67], v[66:67], v[82:83] op_sel_hi:[1,0]
	v_lshl_add_u64 v[84:85], v[148:149], 1, v[84:85]
	v_mul_f32_e32 v78, v78, v78
	v_mul_f32_e32 v75, v75, v75
	v_mul_f32_e32 v76, v76, v76
	v_mul_f32_e32 v77, v77, v77
	v_cvt_pk_bf16_f32 v74, v78, v74
	v_pk_mul_f32 v[72:73], v[72:73], v[82:83] op_sel_hi:[1,0]
	v_pk_mul_f32 v[70:71], v[70:71], v[82:83] op_sel_hi:[1,0]
	v_max_f32_e32 v66, 0, v66
	v_max_f32_e32 v67, 0, v67
	v_max_f32_e32 v68, 0, v68
	v_cvt_pk_bf16_f32 v75, v75, v76
	v_cvt_pk_bf16_f32 v76, v83, v79
	v_cvt_pk_bf16_f32 v77, v80, v77
	global_store_dwordx4 v[84:85], v[74:77], off nt
	v_max_f32_e32 v70, 0, v70
	v_max_f32_e32 v69, 0, v69
	v_mul_f32_e32 v74, v66, v66
	v_max_f32_e32 v66, 0, v71
	v_mul_f32_e32 v71, v67, v67
	v_max_f32_e32 v67, 0, v72
	v_mul_f32_e32 v72, v68, v68
	v_max_f32_e32 v68, 0, v73
	v_mul_f32_e32 v66, v66, v66
	v_mul_f32_e32 v67, v67, v67
	v_mul_f32_e32 v68, v68, v68
	v_mul_f32_e32 v70, v70, v70
	v_mul_f32_e32 v69, v69, v69
	v_cvt_pk_bf16_f32 v66, v70, v66
	v_cvt_pk_bf16_f32 v67, v67, v68
	v_cvt_pk_bf16_f32 v68, v74, v71
	v_cvt_pk_bf16_f32 v69, v72, v69
	global_store_dwordx4 v[84:85], v[66:69], off offset:64 nt
	s_mov_b64 s[22:23], -1
	s_and_b64 vcc, exec, s[4:5]
	v_add_u32_e32 v68, 0x80, v146
	v_ashrrev_i32_e32 v69, 31, v68
	s_cbranch_vccnz .LBB0_1401
	v_lshlrev_b64 v[66:67], 6, v[68:69]
	v_lshl_add_u64 v[66:67], v[138:139], 0, v[66:67]
	global_load_dwordx4 v[70:73], v[66:67], off
	v_and_b32_e32 v67, 64, v159
	v_xor_b32_e32 v66, 16, v159
	v_add_u32_e32 v74, 64, v67
	v_cmp_lt_i32_e32 vcc, v66, v74
	s_mov_b64 s[22:23], 0
	s_waitcnt vmcnt(0)
	v_mov_b32_e32 v67, v72
	v_cndmask_b32_e32 v66, v159, v66, vcc
	v_lshlrev_b32_e32 v75, 2, v66
	v_mov_b32_e32 v66, v71
	v_mov_b32_e32 v71, v73
	v_pk_add_f32 v[66:67], v[66:67], v[70:71]
	v_xor_b32_e32 v70, 32, v159
	v_add_f32_e32 v66, v66, v67
	ds_bpermute_b32 v67, v75, v66
	v_cmp_lt_i32_e32 vcc, v70, v74
	s_waitcnt lgkmcnt(0)
	v_add_f32_e32 v66, v66, v67
	v_cndmask_b32_e32 v70, v159, v70, vcc
	v_lshlrev_b32_e32 v67, 2, v70
	ds_bpermute_b32 v67, v67, v66
	s_waitcnt lgkmcnt(0)
	v_add_f32_e32 v66, v66, v67
	v_fmamk_f32 v66, v66, 0x3a800000, v156
	v_rsq_f32_e32 v66, v66

; __device__ __forceinline__ unsigned cvt_pk_bf16(float lo, float hi) { unsigned r; asm volatile("v_cvt_pk_bf16_f32 %0, %1, %2" : "=v"(r) : "v"(lo), "v"(hi)); return r; }
;     __device__ __forceinline__ void operator()(const f32x4 (&acc)[2][2][4][2], const Unit& u, int wr, int wc, int fr, int fq) const {
;     ...
;             for (int m = 0; m < 4; ++m) { const int r = row0 + ai * HALF + m * 16;
;                 float rstd;
;                 if (u.idx < UP_TAB_ROUNDS) rstd = tab[u.idx * BM + ai * HALF + wr * 64 + m * 16 + fr];
;                 else { const f32x4 p = *(const f32x4*)(stats + (size_t)r * 16 + 4 * fq); float s = (p[0] + p[1]) + (p[2] + p[3]);
;                     s += __shfl_xor(s, 16); s += __shfl_xor(s, 32); rstd = __builtin_amdgcn_rsqf(s * (1.0f / 1024.0f) + RMS_EPS); }
;                 bf16_t* rowp = H + (size_t)r * 4096 + col0;
; #pragma unroll
;                 for (int bj = 0; bj < 2; ++bj) { f32x4 v0 = acc[ai][bj][m][0] * rstd, v1 = acc[ai][bj][m][1] * rstd;
; #pragma unroll
;                     for (int e = 0; e < 4; ++e) { const float a = fmaxf(v0[e], 0.f), b = fmaxf(v1[e], 0.f); v0[e] = a * a; v1[e] = b * b; }
;                     u32x4 w; w.x = cvt_pk_bf16(v0[0], v0[1]); w.y = cvt_pk_bf16(v0[2], v0[3]); w.z = cvt_pk_bf16(v1[0], v1[1]); w.w = cvt_pk_bf16(v1[2], v1[3]);
;                     __builtin_nontemporal_store(w, (u32x4*)(rowp + bj * HALF)); } }
.LBB0_1403:
	s_waitcnt lgkmcnt(0)
	v_pk_mul_f32 v[58:59], v[58:59], v[66:67] op_sel_hi:[1,0]
	v_pk_mul_f32 v[62:63], v[62:63], v[66:67] op_sel_hi:[1,0]
	v_pk_mul_f32 v[60:61], v[60:61], v[66:67] op_sel_hi:[1,0]
	v_max_f32_e32 v58, 0, v58
	v_lshlrev_b64 v[68:69], 7, v[68:69]
	v_pk_mul_f32 v[64:65], v[64:65], v[66:67] op_sel_hi:[1,0]
	v_mul_f32_e32 v67, v58, v58
	v_max_f32_e32 v58, 0, v63
	v_max_f32_e32 v59, 0, v59
	v_max_f32_e32 v60, 0, v60
	v_lshl_add_u64 v[68:69], s[56:57], 0, v[68:69]
	v_max_f32_e32 v62, 0, v62
	v_mul_f32_e32 v58, v58, v58
	v_mul_f32_e32 v63, v59, v59
	v_max_f32_e32 v59, 0, v64
	v_mul_f32_e32 v64, v60, v60
	v_max_f32_e32 v60, 0, v65
	v_max_f32_e32 v61, 0, v61
	v_pk_mul_f32 v[52:53], v[52:53], v[66:67] op_sel_hi:[1,0]
	v_pk_mul_f32 v[50:51], v[50:51], v[66:67] op_sel_hi:[1,0]
	v_lshl_add_u64 v[68:69], v[148:149], 1, v[68:69]
	v_mul_f32_e32 v62, v62, v62
	v_mul_f32_e32 v59, v59, v59
	v_mul_f32_e32 v60, v60, v60
	v_mul_f32_e32 v61, v61, v61
	v_cvt_pk_bf16_f32 v58, v62, v58
	v_pk_mul_f32 v[56:57], v[56:57], v[66:67] op_sel_hi:[1,0]
	v_pk_mul_f32 v[54:55], v[54:55], v[66:67] op_sel_hi:[1,0]
	v_max_f32_e32 v50, 0, v50
	v_max_f32_e32 v51, 0, v51
	v_max_f32_e32 v52, 0, v52
	v_cvt_pk_bf16_f32 v59, v59, v60
	v_cvt_pk_bf16_f32 v60, v67, v63
	v_cvt_pk_bf16_f32 v61, v64, v61
	global_store_dwordx4 v[68:69], v[58:61], off nt
	v_max_f32_e32 v54, 0, v54
	v_max_f32_e32 v53, 0, v53
	v_mul_f32_e32 v58, v50, v50
	v_max_f32_e32 v50, 0, v55
	v_mul_f32_e32 v55, v51, v51
	v_max_f32_e32 v51, 0, v56
	v_mul_f32_e32 v56, v52, v52
	v_max_f32_e32 v52, 0, v57
	v_mul_f32_e32 v50, v50, v50
	v_mul_f32_e32 v51, v51, v51
	v_mul_f32_e32 v52, v52, v52
	v_mul_f32_e32 v54, v54, v54
	v_mul_f32_e32 v53, v53, v53
	v_cvt_pk_bf16_f32 v50, v54, v50
	v_cvt_pk_bf16_f32 v51, v51, v52
	v_cvt_pk_bf16_f32 v52, v58, v55
	v_cvt_pk_bf16_f32 v53, v56, v53
	global_store_dwordx4 v[68:69], v[50:53], off offset:64 nt
	s_mov_b64 s[22:23], -1
	s_and_b64 vcc, exec, s[4:5]
	v_add_u32_e32 v52, 0x90, v146
	v_ashrrev_i32_e32 v53, 31, v52
	s_cbranch_vccnz .LBB0_1405
	v_lshlrev_b64 v[50:51], 6, v[52:53]
	v_lshl_add_u64 v[50:51], v[138:139], 0, v[50:51]
	global_load_dwordx4 v[54:57], v[50:51], off
	v_and_b32_e32 v51, 64, v159
	v_xor_b32_e32 v50, 16, v159
	v_add_u32_e32 v58, 64, v51
	v_cmp_lt_i32_e32 vcc, v50, v58
	s_mov_b64 s[22:23], 0
	s_waitcnt vmcnt(0)
	v_mov_b32_e32 v51, v56
	v_cndmask_b32_e32 v50, v159, v50, vcc
	v_lshlrev_b32_e32 v59, 2, v50
	v_mov_b32_e32 v50, v55
	v_mov_b32_e32 v55, v57
	v_pk_add_f32 v[50:51], v[50:51], v[54:55]
	v_xor_b32_e32 v54, 32, v159
	v_add_f32_e32 v50, v50, v51
	ds_bpermute_b32 v51, v59, v50
	v_cmp_lt_i32_e32 vcc, v54, v58
	s_waitcnt lgkmcnt(0)
	v_add_f32_e32 v50, v50, v51
	v_cndmask_b32_e32 v54, v159, v54, vcc
	v_lshlrev_b32_e32 v51, 2, v54
	ds_bpermute_b32 v51, v51, v50
	s_waitcnt lgkmcnt(0)
	v_add_f32_e32 v50, v50, v51
	v_fmamk_f32 v50, v50, 0x3a800000, v156
	v_rsq_f32_e32 v50, v50

; __device__ __forceinline__ unsigned cvt_pk_bf16(float lo, float hi) { unsigned r; asm volatile("v_cvt_pk_bf16_f32 %0, %1, %2" : "=v"(r) : "v"(lo), "v"(hi)); return r; }
;     __device__ __forceinline__ void operator()(const f32x4 (&acc)[2][2][4][2], const Unit& u, int wr, int wc, int fr, int fq) const {
;     ...
;             for (int m = 0; m < 4; ++m) { const int r = row0 + ai * HALF + m * 16;
;                 float rstd;
;                 if (u.idx < UP_TAB_ROUNDS) rstd = tab[u.idx * BM + ai * HALF + wr * 64 + m * 16 + fr];
;                 else { const f32x4 p = *(const f32x4*)(stats + (size_t)r * 16 + 4 * fq); float s = (p[0] + p[1]) + (p[2] + p[3]);
;                     s += __shfl_xor(s, 16); s += __shfl_xor(s, 32); rstd = __builtin_amdgcn_rsqf(s * (1.0f / 1024.0f) + RMS_EPS); }
;                 bf16_t* rowp = H + (size_t)r * 4096 + col0;
; #pragma unroll
;                 for (int bj = 0; bj < 2; ++bj) { f32x4 v0 = acc[ai][bj][m][0] * rstd, v1 = acc[ai][bj][m][1] * rstd;
; #pragma unroll
;                     for (int e = 0; e < 4; ++e) { const float a = fmaxf(v0[e], 0.f), b = fmaxf(v1[e], 0.f); v0[e] = a * a; v1[e] = b * b; }
;                     u32x4 w; w.x = cvt_pk_bf16(v0[0], v0[1]); w.y = cvt_pk_bf16(v0[2], v0[3]); w.z = cvt_pk_bf16(v1[0], v1[1]); w.w = cvt_pk_bf16(v1[2], v1[3]);
;                     __builtin_nontemporal_store(w, (u32x4*)(rowp + bj * HALF)); } }
.LBB0_1407:
	s_waitcnt lgkmcnt(0)
	v_pk_mul_f32 v[42:43], v[42:43], v[50:51] op_sel_hi:[1,0]
	v_pk_mul_f32 v[46:47], v[46:47], v[50:51] op_sel_hi:[1,0]
	v_pk_mul_f32 v[44:45], v[44:45], v[50:51] op_sel_hi:[1,0]
	v_max_f32_e32 v42, 0, v42
	v_lshlrev_b64 v[52:53], 7, v[52:53]
	v_pk_mul_f32 v[48:49], v[48:49], v[50:51] op_sel_hi:[1,0]
	v_mul_f32_e32 v51, v42, v42
	v_max_f32_e32 v42, 0, v47
	v_max_f32_e32 v43, 0, v43
	v_max_f32_e32 v44, 0, v44
	v_lshl_add_u64 v[52:53], s[56:57], 0, v[52:53]
	v_max_f32_e32 v46, 0, v46
	v_mul_f32_e32 v42, v42, v42
	v_mul_f32_e32 v47, v43, v43
	v_max_f32_e32 v43, 0, v48
	v_mul_f32_e32 v48, v44, v44
	v_max_f32_e32 v44, 0, v49
	v_max_f32_e32 v45, 0, v45
	v_pk_mul_f32 v[36:37], v[36:37], v[50:51] op_sel_hi:[1,0]
	v_pk_mul_f32 v[34:35], v[34:35], v[50:51] op_sel_hi:[1,0]
	v_lshl_add_u64 v[52:53], v[148:149], 1, v[52:53]
	v_mul_f32_e32 v46, v46, v46
	v_mul_f32_e32 v43, v43, v43
	v_mul_f32_e32 v44, v44, v44
	v_mul_f32_e32 v45, v45, v45
	v_cvt_pk_bf16_f32 v42, v46, v42
	v_pk_mul_f32 v[40:41], v[40:41], v[50:51] op_sel_hi:[1,0]
	v_pk_mul_f32 v[38:39], v[38:39], v[50:51] op_sel_hi:[1,0]
	v_max_f32_e32 v34, 0, v34
	v_max_f32_e32 v35, 0, v35
	v_max_f32_e32 v36, 0, v36
	v_cvt_pk_bf16_f32 v43, v43, v44
	v_cvt_pk_bf16_f32 v44, v51, v47
	v_cvt_pk_bf16_f32 v45, v48, v45
	global_store_dwordx4 v[52:53], v[42:45], off nt
	v_max_f32_e32 v38, 0, v38
	v_max_f32_e32 v37, 0, v37
	v_mul_f32_e32 v42, v34, v34
	v_max_f32_e32 v34, 0, v39
	v_mul_f32_e32 v39, v35, v35
	v_max_f32_e32 v35, 0, v40
	v_mul_f32_e32 v40, v36, v36
	v_max_f32_e32 v36, 0, v41
	v_mul_f32_e32 v34, v34, v34
	v_mul_f32_e32 v35, v35, v35
	v_mul_f32_e32 v36, v36, v36
	v_mul_f32_e32 v38, v38, v38
	v_mul_f32_e32 v37, v37, v37
	v_cvt_pk_bf16_f32 v34, v38, v34
	v_cvt_pk_bf16_f32 v35, v35, v36
	v_cvt_pk_bf16_f32 v36, v42, v39
	v_cvt_pk_bf16_f32 v37, v40, v37
	global_store_dwordx4 v[52:53], v[34:37], off offset:64 nt
	s_mov_b64 s[22:23], -1
	s_and_b64 vcc, exec, s[4:5]
	v_add_u32_e32 v36, 0xa0, v146
	v_ashrrev_i32_e32 v37, 31, v36
	s_cbranch_vccnz .LBB0_1409
	v_lshlrev_b64 v[34:35], 6, v[36:37]
	v_lshl_add_u64 v[34:35], v[138:139], 0, v[34:35]
	global_load_dwordx4 v[38:41], v[34:35], off
	v_and_b32_e32 v35, 64, v159
	v_xor_b32_e32 v34, 16, v159
	v_add_u32_e32 v42, 64, v35
	v_cmp_lt_i32_e32 vcc, v34, v42
	s_mov_b64 s[22:23], 0
	s_waitcnt vmcnt(0)
	v_mov_b32_e32 v35, v40
	v_cndmask_b32_e32 v34, v159, v34, vcc
	v_lshlrev_b32_e32 v43, 2, v34
	v_mov_b32_e32 v34, v39
	v_mov_b32_e32 v39, v41
	v_pk_add_f32 v[34:35], v[34:35], v[38:39]
	v_xor_b32_e32 v38, 32, v159
	v_add_f32_e32 v34, v34, v35
	ds_bpermute_b32 v35, v43, v34
	v_cmp_lt_i32_e32 vcc, v38, v42
	s_waitcnt lgkmcnt(0)
	v_add_f32_e32 v34, v34, v35
	v_cndmask_b32_e32 v38, v159, v38, vcc
	v_lshlrev_b32_e32 v35, 2, v38
	ds_bpermute_b32 v35, v35, v34
	s_waitcnt lgkmcnt(0)
	v_add_f32_e32 v34, v34, v35
	v_fmamk_f32 v34, v34, 0x3a800000, v156
	v_rsq_f32_e32 v34, v34

; __device__ __forceinline__ unsigned cvt_pk_bf16(float lo, float hi) { unsigned r; asm volatile("v_cvt_pk_bf16_f32 %0, %1, %2" : "=v"(r) : "v"(lo), "v"(hi)); return r; }
;     __device__ __forceinline__ void operator()(const f32x4 (&acc)[2][2][4][2], const Unit& u, int wr, int wc, int fr, int fq) const {
;     ...
;             for (int m = 0; m < 4; ++m) { const int r = row0 + ai * HALF + m * 16;
;                 float rstd;
;                 if (u.idx < UP_TAB_ROUNDS) rstd = tab[u.idx * BM + ai * HALF + wr * 64 + m * 16 + fr];
;                 else { const f32x4 p = *(const f32x4*)(stats + (size_t)r * 16 + 4 * fq); float s = (p[0] + p[1]) + (p[2] + p[3]);
;                     s += __shfl_xor(s, 16); s += __shfl_xor(s, 32); rstd = __builtin_amdgcn_rsqf(s * (1.0f / 1024.0f) + RMS_EPS); }
;                 bf16_t* rowp = H + (size_t)r * 4096 + col0;
; #pragma unroll
;                 for (int bj = 0; bj < 2; ++bj) { f32x4 v0 = acc[ai][bj][m][0] * rstd, v1 = acc[ai][bj][m][1] * rstd;
; #pragma unroll
;                     for (int e = 0; e < 4; ++e) { const float a = fmaxf(v0[e], 0.f), b = fmaxf(v1[e], 0.f); v0[e] = a * a; v1[e] = b * b; }
;                     u32x4 w; w.x = cvt_pk_bf16(v0[0], v0[1]); w.y = cvt_pk_bf16(v0[2], v0[3]); w.z = cvt_pk_bf16(v1[0], v1[1]); w.w = cvt_pk_bf16(v1[2], v1[3]);
;                     __builtin_nontemporal_store(w, (u32x4*)(rowp + bj * HALF)); } }
.LBB0_1411:
	s_waitcnt lgkmcnt(0)
	v_pk_mul_f32 v[26:27], v[26:27], v[34:35] op_sel_hi:[1,0]
	v_pk_mul_f32 v[30:31], v[30:31], v[34:35] op_sel_hi:[1,0]
	v_pk_mul_f32 v[28:29], v[28:29], v[34:35] op_sel_hi:[1,0]
	v_max_f32_e32 v26, 0, v26
	v_lshlrev_b64 v[36:37], 7, v[36:37]
	v_pk_mul_f32 v[32:33], v[32:33], v[34:35] op_sel_hi:[1,0]
	v_mul_f32_e32 v35, v26, v26
	v_max_f32_e32 v26, 0, v31
	v_max_f32_e32 v27, 0, v27
	v_max_f32_e32 v28, 0, v28
	v_lshl_add_u64 v[36:37], s[56:57], 0, v[36:37]
	v_max_f32_e32 v30, 0, v30
	v_mul_f32_e32 v26, v26, v26
	v_mul_f32_e32 v31, v27, v27
	v_max_f32_e32 v27, 0, v32
	v_mul_f32_e32 v32, v28, v28
	v_max_f32_e32 v28, 0, v33
	v_max_f32_e32 v29, 0, v29
	v_pk_mul_f32 v[20:21], v[20:21], v[34:35] op_sel_hi:[1,0]
	v_pk_mul_f32 v[18:19], v[18:19], v[34:35] op_sel_hi:[1,0]
	v_lshl_add_u64 v[36:37], v[148:149], 1, v[36:37]
	v_mul_f32_e32 v30, v30, v30
	v_mul_f32_e32 v27, v27, v27
	v_mul_f32_e32 v28, v28, v28
	v_mul_f32_e32 v29, v29, v29
	v_cvt_pk_bf16_f32 v26, v30, v26
	v_pk_mul_f32 v[24:25], v[24:25], v[34:35] op_sel_hi:[1,0]
	v_pk_mul_f32 v[22:23], v[22:23], v[34:35] op_sel_hi:[1,0]
	v_max_f32_e32 v18, 0, v18
	v_max_f32_e32 v19, 0, v19
	v_max_f32_e32 v20, 0, v20
	v_cvt_pk_bf16_f32 v27, v27, v28
	v_cvt_pk_bf16_f32 v28, v35, v31
	v_cvt_pk_bf16_f32 v29, v32, v29
	global_store_dwordx4 v[36:37], v[26:29], off nt
	v_max_f32_e32 v22, 0, v22
	v_max_f32_e32 v21, 0, v21
	v_mul_f32_e32 v26, v18, v18
	v_max_f32_e32 v18, 0, v23
	v_mul_f32_e32 v23, v19, v19
	v_max_f32_e32 v19, 0, v24
	v_mul_f32_e32 v24, v20, v20
	v_max_f32_e32 v20, 0, v25
	v_mul_f32_e32 v18, v18, v18
	v_mul_f32_e32 v19, v19, v19
	v_mul_f32_e32 v20, v20, v20
	v_mul_f32_e32 v22, v22, v22
	v_mul_f32_e32 v21, v21, v21
	v_cvt_pk_bf16_f32 v18, v22, v18
	v_cvt_pk_bf16_f32 v19, v19, v20
	v_cvt_pk_bf16_f32 v20, v26, v23
	v_cvt_pk_bf16_f32 v21, v24, v21
	global_store_dwordx4 v[36:37], v[18:21], off offset:64 nt
	s_mov_b64 s[22:23], -1
	s_and_b64 vcc, exec, s[4:5]
	v_add_u32_e32 v20, 0xb0, v146
	v_ashrrev_i32_e32 v21, 31, v20
	s_cbranch_vccnz .LBB0_1413
	v_lshlrev_b64 v[18:19], 6, v[20:21]
	v_lshl_add_u64 v[18:19], v[138:139], 0, v[18:19]
	global_load_dwordx4 v[22:25], v[18:19], off
	v_and_b32_e32 v19, 64, v159
	v_xor_b32_e32 v18, 16, v159
	v_add_u32_e32 v26, 64, v19
	v_cmp_lt_i32_e32 vcc, v18, v26
	s_mov_b64 s[22:23], 0
	s_waitcnt vmcnt(0)
	v_mov_b32_e32 v19, v24
	v_cndmask_b32_e32 v18, v159, v18, vcc
	v_lshlrev_b32_e32 v27, 2, v18
	v_mov_b32_e32 v18, v23
	v_mov_b32_e32 v23, v25
	v_pk_add_f32 v[18:19], v[18:19], v[22:23]
	v_xor_b32_e32 v22, 32, v159
	v_add_f32_e32 v18, v18, v19
	ds_bpermute_b32 v19, v27, v18
	v_cmp_lt_i32_e32 vcc, v22, v26
	s_waitcnt lgkmcnt(0)
	v_add_f32_e32 v18, v18, v19
	v_cndmask_b32_e32 v22, v159, v22, vcc
	v_lshlrev_b32_e32 v19, 2, v22
	ds_bpermute_b32 v19, v19, v18
	s_waitcnt lgkmcnt(0)
	v_add_f32_e32 v18, v18, v19
	v_fmamk_f32 v18, v18, 0x3a800000, v156
	v_rsq_f32_e32 v18, v18

; __device__ __forceinline__ unsigned cvt_pk_bf16(float lo, float hi) { unsigned r; asm volatile("v_cvt_pk_bf16_f32 %0, %1, %2" : "=v"(r) : "v"(lo), "v"(hi)); return r; }
; #define PG8_BAR __builtin_amdgcn_s_barrier()
;     __device__ __forceinline__ void operator()(const f32x4 (&acc)[2][2][4][2], const Unit& u, int wr, int wc, int fr, int fq) const {
;     ...
;             for (int m = 0; m < 4; ++m) { const int r = row0 + ai * HALF + m * 16;
;                 float rstd;
;                 if (u.idx < UP_TAB_ROUNDS) rstd = tab[u.idx * BM + ai * HALF + wr * 64 + m * 16 + fr];
;                 else { const f32x4 p = *(const f32x4*)(stats + (size_t)r * 16 + 4 * fq); float s = (p[0] + p[1]) + (p[2] + p[3]);
;                     s += __shfl_xor(s, 16); s += __shfl_xor(s, 32); rstd = __builtin_amdgcn_rsqf(s * (1.0f / 1024.0f) + RMS_EPS); }
;                 bf16_t* rowp = H + (size_t)r * 4096 + col0;
; #pragma unroll
;                 for (int bj = 0; bj < 2; ++bj) { f32x4 v0 = acc[ai][bj][m][0] * rstd, v1 = acc[ai][bj][m][1] * rstd;
; #pragma unroll
;                     for (int e = 0; e < 4; ++e) { const float a = fmaxf(v0[e], 0.f), b = fmaxf(v1[e], 0.f); v0[e] = a * a; v1[e] = b * b; }
;                     u32x4 w; w.x = cvt_pk_bf16(v0[0], v0[1]); w.y = cvt_pk_bf16(v0[2], v0[3]); w.z = cvt_pk_bf16(v1[0], v1[1]); w.w = cvt_pk_bf16(v1[2], v1[3]);
;                     __builtin_nontemporal_store(w, (u32x4*)(rowp + bj * HALF)); } }
; template <class Epi, class Sched, bool ALIGN_EPI = false, bool SP2 = false>
; __device__ __forceinline__ void gemm_phase(PG8_LAS unsigned char* lds, const Gemm g, const Sched& S, const Epi& E) {
;     ...
;         if (!has_next) break;
; #pragma unroll
;         for (int a = 0; a < 2; ++a)
; #pragma unroll
;             for (int b = 0; b < 2; ++b)
; #pragma unroll
;                 for (int m = 0; m < 4; ++m)
; #pragma unroll
;                     for (int n = 0; n < 2; ++n) acc[a][b][m][n] = (f32x4){0.f, 0.f, 0.f, 0.f};
;         cur = nxt; cA = nA; cB = nB; ++ui;
;         if constexpr (ALIGN_EPI) { if (wr == 1) PG8_BAR; }
;     }
.LBB0_1415:
	s_waitcnt lgkmcnt(0)
	v_pk_mul_f32 v[10:11], v[10:11], v[18:19] op_sel_hi:[1,0]
	v_pk_mul_f32 v[14:15], v[14:15], v[18:19] op_sel_hi:[1,0]
	v_pk_mul_f32 v[12:13], v[12:13], v[18:19] op_sel_hi:[1,0]
	v_max_f32_e32 v10, 0, v10
	v_lshlrev_b64 v[20:21], 7, v[20:21]
	v_pk_mul_f32 v[16:17], v[16:17], v[18:19] op_sel_hi:[1,0]
	v_mul_f32_e32 v19, v10, v10
	v_max_f32_e32 v10, 0, v15
	v_max_f32_e32 v11, 0, v11
	v_max_f32_e32 v12, 0, v12
	v_lshl_add_u64 v[20:21], s[56:57], 0, v[20:21]
	v_max_f32_e32 v14, 0, v14
	v_mul_f32_e32 v10, v10, v10
	v_mul_f32_e32 v15, v11, v11
	v_max_f32_e32 v11, 0, v16
	v_mul_f32_e32 v16, v12, v12
	v_max_f32_e32 v12, 0, v17
	v_max_f32_e32 v13, 0, v13
	v_pk_mul_f32 v[4:5], v[4:5], v[18:19] op_sel_hi:[1,0]
	v_pk_mul_f32 v[2:3], v[2:3], v[18:19] op_sel_hi:[1,0]
	v_lshl_add_u64 v[20:21], v[148:149], 1, v[20:21]
	v_mul_f32_e32 v14, v14, v14
	v_mul_f32_e32 v11, v11, v11
	v_mul_f32_e32 v12, v12, v12
	v_mul_f32_e32 v13, v13, v13
	v_cvt_pk_bf16_f32 v10, v14, v10
	v_pk_mul_f32 v[8:9], v[8:9], v[18:19] op_sel_hi:[1,0]
	v_pk_mul_f32 v[6:7], v[6:7], v[18:19] op_sel_hi:[1,0]
	v_max_f32_e32 v2, 0, v2
	v_max_f32_e32 v3, 0, v3
	v_max_f32_e32 v4, 0, v4
	v_cvt_pk_bf16_f32 v11, v11, v12
	v_cvt_pk_bf16_f32 v12, v19, v15
	v_cvt_pk_bf16_f32 v13, v16, v13
	global_store_dwordx4 v[20:21], v[10:13], off nt
	v_max_f32_e32 v5, 0, v5
	v_max_f32_e32 v6, 0, v6
	v_mul_f32_e32 v10, v2, v2
	v_max_f32_e32 v2, 0, v7
	v_mul_f32_e32 v7, v3, v3
	v_max_f32_e32 v3, 0, v8
	v_mul_f32_e32 v8, v4, v4
	v_max_f32_e32 v4, 0, v9
	v_mul_f32_e32 v2, v2, v2
	v_mul_f32_e32 v3, v3, v3
	v_mul_f32_e32 v4, v4, v4
	v_mul_f32_e32 v5, v5, v5
	s_andn2_b64 vcc, exec, s[16:17]
	s_mov_b64 s[4:5], -1
	v_mul_f32_e32 v6, v6, v6
	v_cvt_pk_bf16_f32 v2, v6, v2
	v_cvt_pk_bf16_f32 v3, v3, v4
	v_cvt_pk_bf16_f32 v4, v10, v7
	v_cvt_pk_bf16_f32 v5, v8, v5
	global_store_dwordx4 v[20:21], v[2:5], off offset:64 nt
	s_cbranch_vccnz .LBB0_1375
	s_andn2_b64 vcc, exec, s[6:7]
	s_cbranch_vccnz .LBB0_1374
	s_barrier
	s_branch .LBB0_1374
